# attention row-max exchange between wave halves with v_permlane32_swap instead of an LDS bpermute
# speedup vs baseline: 1.0370x; 1.0056x over previous
; __device__ void attn_item(const Params& p, int s_idx, char* smem) {
;     ...
;             float mx = sv[0];
; #pragma unroll
;             for (int i = 1; i < 32; ++i) mx = fmaxf(mx, sv[i]);
;             mx = fmaxf(mx, __shfl_xor(mx, 32));
;             const float mnew = fmaxf(mrun, mx);
;             const float alpha = __builtin_amdgcn_exp2f(mrun - mnew);
;             mrun = mnew;
;             float psum = 0.f;
; #pragma unroll
;             for (int i = 0; i < 32; ++i) { sv[i] = __builtin_amdgcn_exp2f(sv[i] - mnew); psum += sv[i]; }
;             lsum = lsum * alpha + psum;
; #pragma unroll
;             for (int i = 0; i < 16; ++i) { O0[i] *= alpha; O1[i] *= alpha; }
.LBB0_113:
	s_or_b64 exec, exec, s[42:43]
	v_max_f32_e32 v40, v123, v123
	v_max_f32_e32 v41, v122, v122
	v_max_f32_e32 v40, v41, v40
	v_max3_f32 v40, v40, v120, v121
	v_max3_f32 v40, v40, v118, v119
	v_max3_f32 v40, v40, v54, v55
	v_max3_f32 v40, v40, v116, v117
	v_max3_f32 v40, v40, v50, v51
	v_max3_f32 v40, v40, v124, v125
	v_max3_f32 v40, v40, v60, v61
	v_max3_f32 v40, v40, v58, v59
	v_max3_f32 v40, v40, v52, v53
	v_max3_f32 v40, v40, v56, v57
	v_max3_f32 v40, v40, v48, v49
	v_max3_f32 v40, v40, v38, v39
	v_max3_f32 v40, v40, v34, v35
	v_max3_f32 v40, v40, v36, v37
	v_max3_f32 v40, v40, v32, v33
	v_mov_b32_e32 v41, v40
	s_nop 1
	v_permlane32_swap_b32_e32 v41, v40
	s_waitcnt lgkmcnt(0)
	v_max_f32_e32 v42, v40, v41
	v_add_f32_e32 v43, 0xc3190000, v157
	v_cmp_lt_f32_e32 vcc, v42, v43
	s_andn2_b64 s[98:99], exec, vcc
	s_cbranch_scc0 .LBB0_114
	v_cmp_gt_f32_e32 vcc, v42, v157
	s_and_b64 s[98:99], exec, vcc
	v_max3_f32 v41, v157, v40, v41
	v_sub_f32_e32 v40, v122, v41
	v_exp_f32_e32 v62, v40
	v_sub_f32_e32 v40, v123, v41
	v_exp_f32_e32 v63, v40
	v_sub_f32_e32 v43, v120, v41
	v_exp_f32_e32 v120, v43
	v_sub_f32_e32 v43, v121, v41
	v_exp_f32_e32 v121, v43
	v_sub_f32_e32 v43, v118, v41
	v_add_f32_e32 v42, 0, v62
	v_exp_f32_e32 v118, v43
	v_sub_f32_e32 v43, v119, v41
	v_add_f32_e32 v42, v63, v42
	v_exp_f32_e32 v119, v43
	v_sub_f32_e32 v43, v54, v41
	v_add_f32_e32 v42, v120, v42
	v_exp_f32_e32 v122, v43
	v_sub_f32_e32 v43, v55, v41
	v_add_f32_e32 v42, v121, v42
	v_exp_f32_e32 v55, v43
	v_sub_f32_e32 v43, v116, v41
	v_add_f32_e32 v42, v118, v42
	v_exp_f32_e32 v116, v43
	v_sub_f32_e32 v43, v117, v41
	v_add_f32_e32 v42, v119, v42
	v_exp_f32_e32 v117, v43
	v_sub_f32_e32 v43, v50, v41
	v_add_f32_e32 v42, v122, v42
	v_exp_f32_e32 v123, v43
	v_sub_f32_e32 v43, v51, v41
	v_sub_f32_e32 v40, v157, v41
	v_add_f32_e32 v42, v55, v42
	v_exp_f32_e32 v157, v43
	v_sub_f32_e32 v43, v124, v41
	v_add_f32_e32 v42, v116, v42
	v_exp_f32_e32 v124, v43
	v_sub_f32_e32 v43, v125, v41
	v_add_f32_e32 v42, v117, v42
	v_exp_f32_e32 v125, v43
	v_add_f32_e32 v42, v123, v42
	v_add_f32_e32 v42, v157, v42
	v_add_f32_e32 v42, v124, v42
	v_add_f32_e32 v44, v125, v42
	v_sub_f32_e32 v42, v60, v41
	v_exp_f32_e32 v60, v42
	v_sub_f32_e32 v42, v61, v41
	v_exp_f32_e32 v61, v42
	v_sub_f32_e32 v42, v58, v41
	v_exp_f32_e32 v42, v42
	v_sub_f32_e32 v43, v59, v41
	v_exp_f32_e32 v43, v43
	v_add_f32_e32 v44, v60, v44
	v_add_f32_e32 v44, v61, v44
	v_add_f32_e32 v44, v42, v44
	v_add_f32_e32 v50, v43, v44
	v_sub_f32_e32 v44, v52, v41
	v_exp_f32_e32 v44, v44
	v_sub_f32_e32 v45, v53, v41
	v_exp_f32_e32 v45, v45
	v_sub_f32_e32 v46, v56, v41
	v_exp_f32_e32 v46, v46
	v_sub_f32_e32 v47, v57, v41
	v_exp_f32_e32 v47, v47
	v_add_f32_e32 v50, v44, v50
	v_add_f32_e32 v50, v45, v50
	v_sub_f32_e32 v48, v48, v41
	v_add_f32_e32 v50, v46, v50
	v_exp_f32_e32 v160, v48
	v_sub_f32_e32 v48, v49, v41
	v_add_f32_e32 v159, v47, v50
	v_exp_f32_e32 v161, v48
	ds_read_b64_tr_b16 v[48:49], v152 offset:9216
	ds_read_b64_tr_b16 v[50:51], v152 offset:9472
	ds_read_b64_tr_b16 v[56:57], v152 offset:13312
	ds_read_b64_tr_b16 v[58:59], v152 offset:13568
	v_exp_f32_e32 v40, v40
	v_cvt_pk_bf16_f32 v52, v62, v63
	v_cvt_pk_bf16_f32 v53, v120, v121
	v_cvt_pk_bf16_f32 v54, v118, v119
	v_cvt_pk_bf16_f32 v55, v122, v55
	v_sub_f32_e32 v38, v38, v41
	s_cmp_eq_u64 s[98:99], 0
	s_cbranch_scc1 .Lnr1a
	v_pk_mul_f32 v[14:15], v[14:15], v[40:41] op_sel_hi:[1,0]
	v_pk_mul_f32 v[12:13], v[12:13], v[40:41] op_sel_hi:[1,0]
	v_pk_mul_f32 v[10:11], v[10:11], v[40:41] op_sel_hi:[1,0]
	v_pk_mul_f32 v[8:9], v[8:9], v[40:41] op_sel_hi:[1,0]
	v_pk_mul_f32 v[6:7], v[6:7], v[40:41] op_sel_hi:[1,0]
	v_pk_mul_f32 v[4:5], v[4:5], v[40:41] op_sel_hi:[1,0]
	v_pk_mul_f32 v[2:3], v[2:3], v[40:41] op_sel_hi:[1,0]
	v_pk_mul_f32 v[0:1], v[0:1], v[40:41] op_sel_hi:[1,0]
	v_pk_mul_f32 v[30:31], v[30:31], v[40:41] op_sel_hi:[1,0]
	v_pk_mul_f32 v[28:29], v[28:29], v[40:41] op_sel_hi:[1,0]

; __device__ void attn_item(const Params& p, int s_idx, char* smem) {
;     ...
;             float mx = sv[0];
; #pragma unroll
;             for (int i = 1; i < 32; ++i) mx = fmaxf(mx, sv[i]);
;             mx = fmaxf(mx, __shfl_xor(mx, 32));
;             const float mnew = fmaxf(mrun, mx);
;             const float alpha = __builtin_amdgcn_exp2f(mrun - mnew);
;             mrun = mnew;
;             float psum = 0.f;
; #pragma unroll
;             for (int i = 0; i < 32; ++i) { sv[i] = __builtin_amdgcn_exp2f(sv[i] - mnew); psum += sv[i]; }
;             lsum = lsum * alpha + psum;
; #pragma unroll
;             for (int i = 0; i < 16; ++i) { O0[i] *= alpha; O1[i] *= alpha; }
.LBB0_119:
	s_or_b64 exec, exec, s[42:43]
	v_max_f32_e32 v40, v123, v123
	v_max_f32_e32 v41, v122, v122
	v_max_f32_e32 v40, v41, v40
	v_max3_f32 v40, v40, v120, v121
	v_max3_f32 v40, v40, v118, v119
	v_max3_f32 v40, v40, v54, v55
	v_max3_f32 v40, v40, v116, v117
	v_max3_f32 v40, v40, v50, v51
	v_max3_f32 v40, v40, v124, v125
	v_max3_f32 v40, v40, v60, v61
	v_max3_f32 v40, v40, v58, v59
	v_max3_f32 v40, v40, v52, v53
	v_max3_f32 v40, v40, v56, v57
	v_max3_f32 v40, v40, v48, v49
	v_max3_f32 v40, v40, v38, v39
	v_max3_f32 v40, v40, v34, v35
	v_max3_f32 v40, v40, v36, v37
	v_max3_f32 v40, v40, v32, v33
	v_mov_b32_e32 v41, v40
	s_nop 1
	v_permlane32_swap_b32_e32 v41, v40
	s_waitcnt lgkmcnt(0)
	v_max_f32_e32 v42, v40, v41
	v_add_f32_e32 v43, 0xc3190000, v157
	v_cmp_lt_f32_e32 vcc, v42, v43
	s_andn2_b64 s[98:99], exec, vcc
	s_cbranch_scc0 .LBB0_120
	v_cmp_gt_f32_e32 vcc, v42, v157
	s_and_b64 s[98:99], exec, vcc
	v_max3_f32 v41, v157, v40, v41
	v_sub_f32_e32 v40, v122, v41
	v_exp_f32_e32 v62, v40
	v_sub_f32_e32 v40, v123, v41
	v_exp_f32_e32 v63, v40
	v_sub_f32_e32 v43, v120, v41
	v_exp_f32_e32 v120, v43
	v_sub_f32_e32 v43, v121, v41
	v_exp_f32_e32 v121, v43
	v_sub_f32_e32 v43, v118, v41
	v_add_f32_e32 v42, 0, v62
	v_exp_f32_e32 v118, v43
	v_sub_f32_e32 v43, v119, v41
	v_add_f32_e32 v42, v63, v42
	v_exp_f32_e32 v119, v43
	v_sub_f32_e32 v43, v54, v41
	v_add_f32_e32 v42, v120, v42
	v_exp_f32_e32 v122, v43
	v_sub_f32_e32 v43, v55, v41
	v_add_f32_e32 v42, v121, v42
	v_exp_f32_e32 v55, v43
	v_sub_f32_e32 v43, v116, v41
	v_add_f32_e32 v42, v118, v42
	v_exp_f32_e32 v116, v43
	v_sub_f32_e32 v43, v117, v41
	v_add_f32_e32 v42, v119, v42
	v_exp_f32_e32 v117, v43
	v_sub_f32_e32 v43, v50, v41
	v_add_f32_e32 v42, v122, v42
	v_exp_f32_e32 v123, v43
	v_sub_f32_e32 v43, v51, v41
	v_sub_f32_e32 v40, v157, v41
	v_add_f32_e32 v42, v55, v42
	v_exp_f32_e32 v157, v43
	v_sub_f32_e32 v43, v124, v41
	v_add_f32_e32 v42, v116, v42
	v_exp_f32_e32 v124, v43
	v_sub_f32_e32 v43, v125, v41
	v_add_f32_e32 v42, v117, v42
	v_exp_f32_e32 v125, v43
	v_add_f32_e32 v42, v123, v42
	v_add_f32_e32 v42, v157, v42
	v_add_f32_e32 v42, v124, v42
	v_add_f32_e32 v44, v125, v42
	v_sub_f32_e32 v42, v60, v41
	v_exp_f32_e32 v60, v42
	v_sub_f32_e32 v42, v61, v41
	v_exp_f32_e32 v61, v42
	v_sub_f32_e32 v42, v58, v41
	v_exp_f32_e32 v42, v42
	v_sub_f32_e32 v43, v59, v41
	v_exp_f32_e32 v43, v43
	v_add_f32_e32 v44, v60, v44
	v_add_f32_e32 v44, v61, v44
	v_add_f32_e32 v44, v42, v44
	v_add_f32_e32 v50, v43, v44
	v_sub_f32_e32 v44, v52, v41
	v_exp_f32_e32 v44, v44
	v_sub_f32_e32 v45, v53, v41
	v_exp_f32_e32 v45, v45
	v_sub_f32_e32 v46, v56, v41
	v_exp_f32_e32 v46, v46
	v_sub_f32_e32 v47, v57, v41
	v_exp_f32_e32 v47, v47
	v_add_f32_e32 v50, v44, v50
	v_add_f32_e32 v50, v45, v50
	v_sub_f32_e32 v48, v48, v41
	v_add_f32_e32 v50, v46, v50
	v_exp_f32_e32 v160, v48
	v_sub_f32_e32 v48, v49, v41
	v_add_f32_e32 v159, v47, v50
	v_exp_f32_e32 v161, v48
	ds_read_b64_tr_b16 v[48:49], v152 offset:27904
	ds_read_b64_tr_b16 v[50:51], v152 offset:28160
	ds_read_b64_tr_b16 v[56:57], v152 offset:32000
	ds_read_b64_tr_b16 v[58:59], v152 offset:32256
	v_exp_f32_e32 v40, v40
	v_cvt_pk_bf16_f32 v52, v62, v63
	v_cvt_pk_bf16_f32 v53, v120, v121
	v_cvt_pk_bf16_f32 v54, v118, v119
	v_cvt_pk_bf16_f32 v55, v122, v55
	v_sub_f32_e32 v38, v38, v41
	s_cmp_eq_u64 s[98:99], 0
	s_cbranch_scc1 .Lnr1b
	v_pk_mul_f32 v[14:15], v[14:15], v[40:41] op_sel_hi:[1,0]
	v_pk_mul_f32 v[12:13], v[12:13], v[40:41] op_sel_hi:[1,0]
	v_pk_mul_f32 v[10:11], v[10:11], v[40:41] op_sel_hi:[1,0]
	v_pk_mul_f32 v[8:9], v[8:9], v[40:41] op_sel_hi:[1,0]
	v_pk_mul_f32 v[6:7], v[6:7], v[40:41] op_sel_hi:[1,0]
	v_pk_mul_f32 v[4:5], v[4:5], v[40:41] op_sel_hi:[1,0]
	v_pk_mul_f32 v[2:3], v[2:3], v[40:41] op_sel_hi:[1,0]
	v_pk_mul_f32 v[0:1], v[0:1], v[40:41] op_sel_hi:[1,0]
	v_pk_mul_f32 v[30:31], v[30:31], v[40:41] op_sel_hi:[1,0]
	v_pk_mul_f32 v[28:29], v[28:29], v[40:41] op_sel_hi:[1,0]
